# layer-0 residual GEMM epilogues: residual loads issued before the post-loop barrier (barrier moved after the adds), readlane reloads after the loads
# baseline (speedup 1.0000x reference)
.LBB0_749:
	v_lshl_add_u32 v66, s12, 7, v99
	v_ashrrev_i32_e32 v64, 31, v66
	v_cmp_gt_i32_e32 vcc, s93, v66
	v_readlane_b32 s52, v254, 39
	v_add_u32_e32 v68, 0xffffc000, v66
	v_cndmask_b32_e32 v67, 0, v64, vcc
	v_readlane_b32 s53, v254, 40
	v_readlane_b32 s54, v254, 41
	v_readlane_b32 s55, v254, 42
	v_cndmask_b32_e32 v68, v68, v66, vcc
	v_mov_b32_e32 v69, v67
	v_mov_b32_e32 v64, s55
	v_mov_b32_e32 v78, s53
	v_mov_b32_e32 v79, s54
	v_mov_b32_e32 v80, s52
	v_cndmask_b32_e32 v71, v64, v78, vcc
	v_cndmask_b32_e32 v70, v79, v80, vcc
	v_lshlrev_b64 v[68:69], 12, v[68:69]
	v_lshl_add_u64 v[68:69], v[70:71], 0, v[68:69]
	v_lshl_or_b32 v70, s10, 7, v98
	v_ashrrev_i32_e32 v71, 31, v70
	v_lshlrev_b64 v[72:73], 2, v[70:71]
	v_lshl_add_u64 v[74:75], v[68:69], 0, v[72:73]
	v_or_b32_e32 v184, 16, v66
	v_cmp_gt_i32_e32 vcc, s93, v184
	v_add_u32_e32 v170, 0xffffc010, v66
	v_mov_b32_e32 v171, 0
	v_cndmask_b32_e32 v170, v170, v184, vcc
	v_cndmask_b32_e32 v187, v64, v78, vcc
	v_cndmask_b32_e32 v186, v79, v80, vcc
	v_lshlrev_b64 v[170:171], 12, v[170:171]
	v_lshl_add_u64 v[170:171], v[186:187], 0, v[170:171]
	v_lshl_add_u64 v[170:171], v[170:171], 0, v[72:73]
	v_mov_b32_e32 v178, v184
	v_mov_b32_e32 v179, 0
	v_or_b32_e32 v184, 32, v66
	v_cmp_gt_i32_e32 vcc, s93, v184
	v_add_u32_e32 v172, 0xffffc020, v66
	v_mov_b32_e32 v173, 0
	v_cndmask_b32_e32 v172, v172, v184, vcc
	v_cndmask_b32_e32 v187, v64, v78, vcc
	v_cndmask_b32_e32 v186, v79, v80, vcc
	v_lshlrev_b64 v[172:173], 12, v[172:173]
	v_lshl_add_u64 v[172:173], v[186:187], 0, v[172:173]
	v_lshl_add_u64 v[172:173], v[172:173], 0, v[72:73]
	v_mov_b32_e32 v180, v184
	v_mov_b32_e32 v181, 0
	v_or_b32_e32 v184, 48, v66
	v_cmp_gt_i32_e32 vcc, s93, v184
	v_add_u32_e32 v176, 0xffffc030, v66
	v_mov_b32_e32 v177, 0
	v_cndmask_b32_e32 v176, v176, v184, vcc
	v_cndmask_b32_e32 v187, v64, v78, vcc
	v_cndmask_b32_e32 v186, v79, v80, vcc
	v_lshlrev_b64 v[176:177], 12, v[176:177]
	v_lshl_add_u64 v[176:177], v[186:187], 0, v[176:177]
	v_lshl_add_u64 v[176:177], v[176:177], 0, v[72:73]
	v_mov_b32_e32 v182, v184
	v_mov_b32_e32 v183, 0
	global_load_dwordx4 v[82:85], v[74:75], off nt
	global_load_dwordx4 v[86:89], v[74:75], off offset:64 nt
	global_load_dwordx4 v[90:93], v[74:75], off offset:128 nt
	global_load_dwordx4 v[94:97], v[74:75], off offset:192 nt
	global_load_dwordx4 v[122:125], v[170:171], off nt
	global_load_dwordx4 v[126:129], v[170:171], off offset:64 nt
	global_load_dwordx4 v[130:133], v[170:171], off offset:128 nt
	global_load_dwordx4 v[134:137], v[170:171], off offset:192 nt
	global_load_dwordx4 v[138:141], v[172:173], off nt
	global_load_dwordx4 v[142:145], v[172:173], off offset:64 nt
	global_load_dwordx4 v[146:149], v[172:173], off offset:128 nt
	global_load_dwordx4 v[150:153], v[172:173], off offset:192 nt
	global_load_dwordx4 v[154:157], v[176:177], off nt
	global_load_dwordx4 v[158:161], v[176:177], off offset:64 nt
	global_load_dwordx4 v[162:165], v[176:177], off offset:128 nt
	global_load_dwordx4 v[166:169], v[176:177], off offset:192 nt
	v_readlane_b32 s12, v254, 3
	v_lshlrev_b64 v[76:77], 12, v[66:67]
	v_readlane_b32 s26, v254, 17
	v_readlane_b32 s27, v254, 18
	s_add_i32 s3, s3, s91
	s_add_i32 s92, s92, s28
	v_lshl_add_u64 v[76:77], s[26:27], 0, v[76:77]
	v_lshl_add_u64 v[76:77], v[76:77], 0, v[72:73]
	s_cmpk_gt_i32 s3, 0x87
	v_readlane_b32 s56, v254, 43
	v_readlane_b32 s57, v254, 44
	v_readlane_b32 s58, v254, 45
	v_readlane_b32 s59, v254, 46
	v_readlane_b32 s60, v254, 47
	v_readlane_b32 s61, v254, 48
	v_readlane_b32 s62, v254, 49
	v_readlane_b32 s63, v254, 50
	v_readlane_b32 s64, v254, 51
	v_readlane_b32 s65, v254, 52
	v_readlane_b32 s66, v254, 53
	v_readlane_b32 s67, v254, 54
	v_readlane_b32 s13, v254, 4
	v_readlane_b32 s14, v254, 5
	v_readlane_b32 s15, v254, 6
	v_readlane_b32 s16, v254, 7
	v_readlane_b32 s17, v254, 8
	v_readlane_b32 s18, v254, 9
	v_readlane_b32 s19, v254, 10
	v_readlane_b32 s20, v254, 11
	v_readlane_b32 s21, v254, 12
	v_readlane_b32 s22, v254, 13
	v_readlane_b32 s23, v254, 14
	v_readlane_b32 s24, v254, 15
	v_readlane_b32 s25, v254, 16
	v_lshlrev_b64 v[178:179], 12, v[178:179]
	v_lshl_add_u64 v[178:179], s[26:27], 0, v[178:179]
	v_lshl_add_u64 v[178:179], v[178:179], 0, v[72:73]
	v_lshlrev_b64 v[180:181], 12, v[180:181]
	v_lshl_add_u64 v[180:181], s[26:27], 0, v[180:181]
	v_lshl_add_u64 v[180:181], v[180:181], 0, v[72:73]
	v_lshlrev_b64 v[182:183], 12, v[182:183]
	v_lshl_add_u64 v[182:183], s[26:27], 0, v[182:183]
	v_lshl_add_u64 v[182:183], v[182:183], 0, v[72:73]
	s_waitcnt vmcnt(15)
	v_pk_add_f32 v[60:61], v[60:61], v[82:83]
	v_pk_add_f32 v[62:63], v[62:63], v[84:85]
	s_waitcnt vmcnt(14)
	v_pk_add_f32 v[56:57], v[56:57], v[86:87]
	v_pk_add_f32 v[58:59], v[58:59], v[88:89]
	s_waitcnt vmcnt(13)
	v_pk_add_f32 v[52:53], v[52:53], v[90:91]
	v_pk_add_f32 v[54:55], v[54:55], v[92:93]
	s_waitcnt vmcnt(12)
	v_pk_add_f32 v[48:49], v[48:49], v[94:95]
	v_pk_add_f32 v[50:51], v[50:51], v[96:97]
	s_waitcnt vmcnt(11)
	v_pk_add_f32 v[44:45], v[44:45], v[122:123]
	v_pk_add_f32 v[46:47], v[46:47], v[124:125]
	s_waitcnt vmcnt(10)
	v_pk_add_f32 v[40:41], v[40:41], v[126:127]
	v_pk_add_f32 v[42:43], v[42:43], v[128:129]
	s_waitcnt vmcnt(9)
	v_pk_add_f32 v[36:37], v[36:37], v[130:131]
	v_pk_add_f32 v[38:39], v[38:39], v[132:133]
	s_waitcnt vmcnt(8)
	v_pk_add_f32 v[32:33], v[32:33], v[134:135]
	v_pk_add_f32 v[34:35], v[34:35], v[136:137]
	s_waitcnt vmcnt(7)
	v_pk_add_f32 v[28:29], v[28:29], v[138:139]
	v_pk_add_f32 v[30:31], v[30:31], v[140:141]
	s_waitcnt vmcnt(6)
	v_pk_add_f32 v[24:25], v[24:25], v[142:143]
	v_pk_add_f32 v[26:27], v[26:27], v[144:145]
	s_waitcnt vmcnt(5)
	v_pk_add_f32 v[20:21], v[20:21], v[146:147]
	v_pk_add_f32 v[22:23], v[22:23], v[148:149]
	s_waitcnt vmcnt(4)
	v_pk_add_f32 v[16:17], v[16:17], v[150:151]
	v_pk_add_f32 v[18:19], v[18:19], v[152:153]
	s_waitcnt vmcnt(3)
	v_pk_add_f32 v[12:13], v[12:13], v[154:155]
	v_pk_add_f32 v[14:15], v[14:15], v[156:157]
	s_waitcnt vmcnt(2)
	v_pk_add_f32 v[8:9], v[8:9], v[158:159]
	v_pk_add_f32 v[10:11], v[10:11], v[160:161]
	s_waitcnt vmcnt(1)
	v_pk_add_f32 v[4:5], v[4:5], v[162:163]
	v_pk_add_f32 v[6:7], v[6:7], v[164:165]
	s_waitcnt vmcnt(0)
	v_pk_add_f32 v[0:1], v[0:1], v[166:167]
	v_pk_add_f32 v[2:3], v[2:3], v[168:169]
	s_barrier
	global_store_dwordx4 v[76:77], v[60:63], off
	global_store_dwordx4 v[76:77], v[56:59], off offset:64
	global_store_dwordx4 v[76:77], v[52:55], off offset:128
	global_store_dwordx4 v[76:77], v[48:51], off offset:192
	global_store_dwordx4 v[178:179], v[44:47], off
	global_store_dwordx4 v[178:179], v[40:43], off offset:64
	global_store_dwordx4 v[178:179], v[36:39], off offset:128
	global_store_dwordx4 v[178:179], v[32:35], off offset:192
	global_store_dwordx4 v[180:181], v[28:31], off
	global_store_dwordx4 v[180:181], v[24:27], off offset:64
	global_store_dwordx4 v[180:181], v[20:23], off offset:128
	global_store_dwordx4 v[180:181], v[16:19], off offset:192
	global_store_dwordx4 v[182:183], v[12:15], off
	global_store_dwordx4 v[182:183], v[8:11], off offset:64
	global_store_dwordx4 v[182:183], v[4:7], off offset:128
	global_store_dwordx4 v[182:183], v[0:3], off offset:192
	s_cbranch_scc1 .LBB0_754

.LBB0_950:
	v_lshl_add_u32 v66, s92, 7, v99
	v_ashrrev_i32_e32 v67, 31, v66
	v_readlane_b32 s12, v254, 3
	v_lshlrev_b64 v[68:69], 12, v[66:67]
	v_readlane_b32 s26, v254, 17
	v_readlane_b32 s27, v254, 18
	v_lshl_add_u64 v[70:71], s[26:27], 0, v[68:69]
	v_lshl_or_b32 v68, s91, 7, v98
	v_ashrrev_i32_e32 v69, 31, v68
	v_lshlrev_b64 v[68:69], 2, v[68:69]
	v_lshl_add_u64 v[74:75], v[70:71], 0, v[68:69]
	v_or_b32_e32 v170, 16, v66
	v_ashrrev_i32_e32 v171, 31, v170
	v_lshlrev_b64 v[170:171], 12, v[170:171]
	v_lshl_add_u64 v[170:171], s[26:27], 0, v[170:171]
	v_lshl_add_u64 v[170:171], v[170:171], 0, v[68:69]
	v_or_b32_e32 v172, 32, v66
	v_ashrrev_i32_e32 v173, 31, v172
	v_lshlrev_b64 v[172:173], 12, v[172:173]
	v_lshl_add_u64 v[172:173], s[26:27], 0, v[172:173]
	v_lshl_add_u64 v[172:173], v[172:173], 0, v[68:69]
	v_or_b32_e32 v176, 48, v66
	v_ashrrev_i32_e32 v177, 31, v176
	v_lshlrev_b64 v[176:177], 12, v[176:177]
	v_lshl_add_u64 v[176:177], s[26:27], 0, v[176:177]
	v_lshl_add_u64 v[176:177], v[176:177], 0, v[68:69]
	global_load_dwordx4 v[82:85], v[74:75], off
	global_load_dwordx4 v[86:89], v[74:75], off offset:64
	global_load_dwordx4 v[90:93], v[74:75], off offset:128
	global_load_dwordx4 v[94:97], v[74:75], off offset:192
	global_load_dwordx4 v[122:125], v[170:171], off
	global_load_dwordx4 v[126:129], v[170:171], off offset:64
	global_load_dwordx4 v[130:133], v[170:171], off offset:128
	global_load_dwordx4 v[134:137], v[170:171], off offset:192
	global_load_dwordx4 v[138:141], v[172:173], off
	global_load_dwordx4 v[142:145], v[172:173], off offset:64
	global_load_dwordx4 v[146:149], v[172:173], off offset:128
	global_load_dwordx4 v[150:153], v[172:173], off offset:192
	global_load_dwordx4 v[154:157], v[176:177], off
	global_load_dwordx4 v[158:161], v[176:177], off offset:64
	global_load_dwordx4 v[162:165], v[176:177], off offset:128
	global_load_dwordx4 v[166:169], v[176:177], off offset:192
	s_add_i32 s3, s3, s85
	s_add_i32 s90, s90, s28
	s_cmpk_gt_i32 s3, 0x87
	v_readlane_b32 s13, v254, 4
	v_readlane_b32 s14, v254, 5
	v_readlane_b32 s15, v254, 6
	v_readlane_b32 s16, v254, 7
	v_readlane_b32 s17, v254, 8
	v_readlane_b32 s18, v254, 9
	v_readlane_b32 s19, v254, 10
	v_readlane_b32 s20, v254, 11
	v_readlane_b32 s21, v254, 12
	v_readlane_b32 s22, v254, 13
	v_readlane_b32 s23, v254, 14
	v_readlane_b32 s24, v254, 15
	v_readlane_b32 s25, v254, 16
	s_waitcnt vmcnt(15)
	v_pk_add_f32 v[60:61], v[60:61], v[82:83]
	v_pk_add_f32 v[62:63], v[62:63], v[84:85]
	s_waitcnt vmcnt(14)
	v_pk_add_f32 v[56:57], v[56:57], v[86:87]
	v_pk_add_f32 v[58:59], v[58:59], v[88:89]
	s_waitcnt vmcnt(13)
	v_pk_add_f32 v[52:53], v[52:53], v[90:91]
	v_pk_add_f32 v[54:55], v[54:55], v[92:93]
	s_waitcnt vmcnt(12)
	v_pk_add_f32 v[48:49], v[48:49], v[94:95]
	v_pk_add_f32 v[50:51], v[50:51], v[96:97]
	s_waitcnt vmcnt(11)
	v_pk_add_f32 v[44:45], v[44:45], v[122:123]
	v_pk_add_f32 v[46:47], v[46:47], v[124:125]
	s_waitcnt vmcnt(10)
	v_pk_add_f32 v[40:41], v[40:41], v[126:127]
	v_pk_add_f32 v[42:43], v[42:43], v[128:129]
	s_waitcnt vmcnt(9)
	v_pk_add_f32 v[36:37], v[36:37], v[130:131]
	v_pk_add_f32 v[38:39], v[38:39], v[132:133]
	s_waitcnt vmcnt(8)
	v_pk_add_f32 v[32:33], v[32:33], v[134:135]
	v_pk_add_f32 v[34:35], v[34:35], v[136:137]
	s_waitcnt vmcnt(7)
	v_pk_add_f32 v[28:29], v[28:29], v[138:139]
	v_pk_add_f32 v[30:31], v[30:31], v[140:141]
	s_waitcnt vmcnt(6)
	v_pk_add_f32 v[24:25], v[24:25], v[142:143]
	v_pk_add_f32 v[26:27], v[26:27], v[144:145]
	s_waitcnt vmcnt(5)
	v_pk_add_f32 v[20:21], v[20:21], v[146:147]
	v_pk_add_f32 v[22:23], v[22:23], v[148:149]
	s_waitcnt vmcnt(4)
	v_pk_add_f32 v[16:17], v[16:17], v[150:151]
	v_pk_add_f32 v[18:19], v[18:19], v[152:153]
	s_waitcnt vmcnt(3)
	v_pk_add_f32 v[12:13], v[12:13], v[154:155]
	v_pk_add_f32 v[14:15], v[14:15], v[156:157]
	s_waitcnt vmcnt(2)
	v_pk_add_f32 v[8:9], v[8:9], v[158:159]
	v_pk_add_f32 v[10:11], v[10:11], v[160:161]
	s_waitcnt vmcnt(1)
	v_pk_add_f32 v[4:5], v[4:5], v[162:163]
	v_pk_add_f32 v[6:7], v[6:7], v[164:165]
	s_waitcnt vmcnt(0)
	v_pk_add_f32 v[0:1], v[0:1], v[166:167]
	v_pk_add_f32 v[2:3], v[2:3], v[168:169]
	s_barrier
	global_store_dwordx4 v[74:75], v[60:63], off
	global_store_dwordx4 v[74:75], v[56:59], off offset:64
	global_store_dwordx4 v[74:75], v[52:55], off offset:128
	global_store_dwordx4 v[74:75], v[48:51], off offset:192
	global_store_dwordx4 v[170:171], v[44:47], off
	global_store_dwordx4 v[170:171], v[40:43], off offset:64
	global_store_dwordx4 v[170:171], v[36:39], off offset:128
	global_store_dwordx4 v[170:171], v[32:35], off offset:192
	global_store_dwordx4 v[172:173], v[28:31], off
	global_store_dwordx4 v[172:173], v[24:27], off offset:64
	global_store_dwordx4 v[172:173], v[20:23], off offset:128
	global_store_dwordx4 v[172:173], v[16:19], off offset:192
	global_store_dwordx4 v[176:177], v[12:15], off
	global_store_dwordx4 v[176:177], v[8:11], off offset:64
	global_store_dwordx4 v[176:177], v[4:7], off offset:128
	global_store_dwordx4 v[176:177], v[0:3], off offset:192
	s_cbranch_scc1 .LBB0_955
